# attention: lazy running max (MFMA C-init = -m_ref, exp2 without per-element subtraction, rescale only when tile max exceeds reference by >8; exact softmax by shift invariance) + previous
# speedup vs baseline: 1.0043x; 1.0043x over previous
.LBB0_659:
	s_waitcnt vmcnt(4)
	v_add3_u32 v124, 0, v169, v170
	ds_read_b128 v[32:35], v124
	s_waitcnt vmcnt(3)
	ds_read_b128 v[120:123], v124 offset:32
	s_waitcnt lgkmcnt(1)
	v_mfma_f32_32x32x16_bf16 v[80:95], v[32:35], v[108:111], v[194:209]
	ds_read_b128 v[32:35], v124 offset:6656
	s_waitcnt lgkmcnt(1)
	v_mfma_f32_32x32x16_bf16 v[80:95], v[120:123], v[104:107], v[80:95]
	s_waitcnt lgkmcnt(0)
	v_mfma_f32_32x32x16_bf16 v[64:79], v[32:35], v[108:111], v[194:209]
	ds_read_b128 v[32:35], v124 offset:13312
	s_waitcnt lgkmcnt(0)
	v_mfma_f32_32x32x16_bf16 v[48:63], v[32:35], v[108:111], v[194:209]
	ds_read_b128 v[32:35], v124 offset:19968
	s_waitcnt lgkmcnt(0)
	v_mfma_f32_32x32x16_bf16 v[32:47], v[32:35], v[108:111], v[194:209]
	ds_read_b128 v[108:111], v124 offset:6688
	s_waitcnt lgkmcnt(0)
	v_mfma_f32_32x32x16_bf16 v[64:79], v[108:111], v[104:107], v[64:79]
	ds_read_b128 v[108:111], v124 offset:13344
	s_waitcnt lgkmcnt(0)
	v_mfma_f32_32x32x16_bf16 v[48:63], v[108:111], v[104:107], v[48:63]
	ds_read_b128 v[108:111], v124 offset:20000
	s_waitcnt lgkmcnt(0)
	v_mfma_f32_32x32x16_bf16 v[32:47], v[108:111], v[104:107], v[32:47]
	ds_read_b128 v[104:107], v124 offset:64
	s_waitcnt lgkmcnt(0)
	v_mfma_f32_32x32x16_bf16 v[80:95], v[104:107], v[100:103], v[80:95]
	ds_read_b128 v[104:107], v124 offset:6720
	s_waitcnt lgkmcnt(0)
	v_mfma_f32_32x32x16_bf16 v[64:79], v[104:107], v[100:103], v[64:79]
	ds_read_b128 v[104:107], v124 offset:13376
	s_waitcnt lgkmcnt(0)
	v_mfma_f32_32x32x16_bf16 v[48:63], v[104:107], v[100:103], v[48:63]
	ds_read_b128 v[104:107], v124 offset:20032
	s_waitcnt lgkmcnt(0)
	v_mfma_f32_32x32x16_bf16 v[32:47], v[104:107], v[100:103], v[32:47]
	ds_read_b128 v[100:103], v124 offset:96
	s_waitcnt lgkmcnt(0)
	v_mfma_f32_32x32x16_bf16 v[80:95], v[100:103], v[96:99], v[80:95]
	ds_read_b128 v[100:103], v124 offset:6752
	s_waitcnt lgkmcnt(0)
	v_mfma_f32_32x32x16_bf16 v[64:79], v[100:103], v[96:99], v[64:79]
	ds_read_b128 v[100:103], v124 offset:13408
	s_waitcnt lgkmcnt(0)
	v_mfma_f32_32x32x16_bf16 v[48:63], v[100:103], v[96:99], v[48:63]
	ds_read_b128 v[100:103], v124 offset:20064
	s_waitcnt lgkmcnt(0)
	v_mfma_f32_32x32x16_bf16 v[32:47], v[100:103], v[96:99], v[32:47]
	ds_read_b128 v[96:99], v124 offset:128
	s_waitcnt lgkmcnt(0)
	v_mfma_f32_32x32x16_bf16 v[80:95], v[96:99], v[112:115], v[80:95]
	ds_read_b128 v[96:99], v124 offset:6784
	s_waitcnt lgkmcnt(0)
	v_mfma_f32_32x32x16_bf16 v[64:79], v[96:99], v[112:115], v[64:79]
	ds_read_b128 v[96:99], v124 offset:13440
	s_waitcnt lgkmcnt(0)
	v_mfma_f32_32x32x16_bf16 v[48:63], v[96:99], v[112:115], v[48:63]
	ds_read_b128 v[96:99], v124 offset:160
	ds_read_b128 v[100:103], v124 offset:13472
	ds_read_b128 v[104:107], v124 offset:6816
	s_waitcnt lgkmcnt(2)
	v_mfma_f32_32x32x16_bf16 v[80:95], v[96:99], v[116:119], v[80:95]
	ds_read_b128 v[96:99], v124 offset:20128
	ds_read_b128 v[108:111], v124 offset:20096
	s_waitcnt lgkmcnt(2)
	v_mfma_f32_32x32x16_bf16 v[64:79], v[104:107], v[116:119], v[64:79]
	s_nop 7
	v_max_f32_e32 v120, v81, v81
	v_max_f32_e32 v121, v80, v80
	v_max_f32_e32 v120, v121, v120
	v_max3_f32 v120, v120, v82, v83
	v_max3_f32 v120, v120, v84, v85
	v_max3_f32 v104, v120, v86, v87
	v_max3_f32 v104, v104, v88, v89
	v_max3_f32 v104, v104, v90, v91
	v_max3_f32 v104, v104, v92, v93
	v_max3_f32 v104, v104, v94, v95
	v_max3_f32 v104, v104, v64, v65
	v_mfma_f32_32x32x16_bf16 v[48:63], v[100:103], v[116:119], v[48:63]
	v_max3_f32 v104, v104, v66, v67
	v_max3_f32 v100, v104, v68, v69
	v_max3_f32 v100, v100, v70, v71
	v_max3_f32 v100, v100, v72, v73
	v_max3_f32 v100, v100, v74, v75
	v_max3_f32 v100, v100, v76, v77
	v_max3_f32 v100, v100, v78, v79
	s_waitcnt lgkmcnt(0)
	v_mfma_f32_32x32x16_bf16 v[32:47], v[108:111], v[112:115], v[32:47]
	s_nop 2
	v_max3_f32 v100, v100, v48, v49
	v_max3_f32 v100, v100, v50, v51
	v_max3_f32 v100, v100, v52, v53
	v_max3_f32 v100, v100, v54, v55
	v_max3_f32 v100, v100, v56, v57
	v_max3_f32 v100, v100, v58, v59
	v_max3_f32 v100, v100, v60, v61
	v_mfma_f32_32x32x16_bf16 v[32:47], v[96:99], v[116:119], v[32:47]
	v_max3_f32 v100, v100, v62, v63
	s_nop 10
	v_max3_f32 v96, v100, v32, v33
	v_max3_f32 v96, v96, v34, v35
	v_max3_f32 v96, v96, v36, v37
	v_max3_f32 v96, v96, v38, v39
	v_max3_f32 v96, v96, v40, v41
	v_max3_f32 v96, v96, v42, v43
	v_max3_f32 v96, v96, v44, v45
	v_max3_f32 v96, v96, v46, v47
	ds_bpermute_b32 v97, v147, v96
	s_waitcnt lgkmcnt(0)
	v_max_f32_e32 v96, v96, v97
	v_cmp_gt_f32_e32 vcc, v96, v210
	s_cbranch_vccz .LBB0_661
	s_nop 1
	v_cndmask_b32_e32 v96, 0, v96, vcc
	v_exp_f32_e64 v98, -v96
	s_nop 0
	v_pk_mul_f32 v[30:31], v[30:31], v[98:99] op_sel_hi:[1,0]
	v_pk_mul_f32 v[28:29], v[28:29], v[98:99] op_sel_hi:[1,0]
	v_pk_mul_f32 v[26:27], v[26:27], v[98:99] op_sel_hi:[1,0]
	v_pk_mul_f32 v[24:25], v[24:25], v[98:99] op_sel_hi:[1,0]
	v_pk_mul_f32 v[22:23], v[22:23], v[98:99] op_sel_hi:[1,0]
	v_pk_mul_f32 v[20:21], v[20:21], v[98:99] op_sel_hi:[1,0]
	v_pk_mul_f32 v[18:19], v[18:19], v[98:99] op_sel_hi:[1,0]
	v_pk_mul_f32 v[16:17], v[16:17], v[98:99] op_sel_hi:[1,0]
	v_pk_mul_f32 v[14:15], v[14:15], v[98:99] op_sel_hi:[1,0]
	v_pk_mul_f32 v[12:13], v[12:13], v[98:99] op_sel_hi:[1,0]
	v_pk_mul_f32 v[10:11], v[10:11], v[98:99] op_sel_hi:[1,0]
	v_pk_mul_f32 v[8:9], v[8:9], v[98:99] op_sel_hi:[1,0]
	v_pk_mul_f32 v[6:7], v[6:7], v[98:99] op_sel_hi:[1,0]
	v_pk_mul_f32 v[4:5], v[4:5], v[98:99] op_sel_hi:[1,0]
	v_pk_mul_f32 v[2:3], v[2:3], v[98:99] op_sel_hi:[1,0]
	v_pk_mul_f32 v[0:1], v[0:1], v[98:99] op_sel_hi:[1,0]
	v_mul_f32_e32 v149, v149, v98
	v_sub_f32_e32 v80, v80, v96
	v_sub_f32_e32 v81, v81, v96
	v_sub_f32_e32 v82, v82, v96
	v_sub_f32_e32 v83, v83, v96
	v_sub_f32_e32 v84, v84, v96
	v_sub_f32_e32 v85, v85, v96
	v_sub_f32_e32 v86, v86, v96
	v_sub_f32_e32 v87, v87, v96
	v_sub_f32_e32 v88, v88, v96
	v_sub_f32_e32 v89, v89, v96
	v_sub_f32_e32 v90, v90, v96
	v_sub_f32_e32 v91, v91, v96
	v_sub_f32_e32 v92, v92, v96
	v_sub_f32_e32 v93, v93, v96
	v_sub_f32_e32 v94, v94, v96
	v_sub_f32_e32 v95, v95, v96
	v_sub_f32_e32 v64, v64, v96
	v_sub_f32_e32 v65, v65, v96
	v_sub_f32_e32 v66, v66, v96
	v_sub_f32_e32 v67, v67, v96
	v_sub_f32_e32 v68, v68, v96
	v_sub_f32_e32 v69, v69, v96
	v_sub_f32_e32 v70, v70, v96
	v_sub_f32_e32 v71, v71, v96
	v_sub_f32_e32 v72, v72, v96
	v_sub_f32_e32 v73, v73, v96
	v_sub_f32_e32 v74, v74, v96
	v_sub_f32_e32 v75, v75, v96
	v_sub_f32_e32 v76, v76, v96
	v_sub_f32_e32 v77, v77, v96
	v_sub_f32_e32 v78, v78, v96
	v_sub_f32_e32 v79, v79, v96
	v_sub_f32_e32 v48, v48, v96
	v_sub_f32_e32 v49, v49, v96
	v_sub_f32_e32 v50, v50, v96
	v_sub_f32_e32 v51, v51, v96
	v_sub_f32_e32 v52, v52, v96
	v_sub_f32_e32 v53, v53, v96
	v_sub_f32_e32 v54, v54, v96
	v_sub_f32_e32 v55, v55, v96
	v_sub_f32_e32 v56, v56, v96
	v_sub_f32_e32 v57, v57, v96
	v_sub_f32_e32 v58, v58, v96
	v_sub_f32_e32 v59, v59, v96
	v_sub_f32_e32 v60, v60, v96
	v_sub_f32_e32 v61, v61, v96
	v_sub_f32_e32 v62, v62, v96
	v_sub_f32_e32 v63, v63, v96
	v_sub_f32_e32 v32, v32, v96
	v_sub_f32_e32 v33, v33, v96
	v_sub_f32_e32 v34, v34, v96
	v_sub_f32_e32 v35, v35, v96
	v_sub_f32_e32 v36, v36, v96
	v_sub_f32_e32 v37, v37, v96
	v_sub_f32_e32 v38, v38, v96
	v_sub_f32_e32 v39, v39, v96
	v_sub_f32_e32 v40, v40, v96
	v_sub_f32_e32 v41, v41, v96
	v_sub_f32_e32 v42, v42, v96
	v_sub_f32_e32 v43, v43, v96
	v_sub_f32_e32 v44, v44, v96
	v_sub_f32_e32 v45, v45, v96
	v_sub_f32_e32 v46, v46, v96
	v_sub_f32_e32 v47, v47, v96
.LBB0_661:
	s_waitcnt lgkmcnt(0)
	s_barrier
	v_exp_f32_e32 v80, v80
	v_exp_f32_e32 v81, v81
	v_exp_f32_e32 v82, v82
	v_exp_f32_e32 v83, v83
	v_add_f32_e32 v97, 0, v80
	v_exp_f32_e32 v84, v84
	v_add_f32_e32 v97, v81, v97
	v_exp_f32_e32 v85, v85
	v_add_f32_e32 v97, v82, v97
	v_exp_f32_e32 v86, v86
	v_add_f32_e32 v97, v83, v97
	v_exp_f32_e32 v87, v87
	v_add_f32_e32 v97, v84, v97
	v_exp_f32_e32 v88, v88
	v_add_f32_e32 v97, v85, v97
	v_exp_f32_e32 v89, v89
	v_add_f32_e32 v97, v86, v97
	v_exp_f32_e32 v90, v90
	v_add_f32_e32 v97, v87, v97
	v_exp_f32_e32 v91, v91
	v_add_f32_e32 v97, v88, v97
	v_exp_f32_e32 v92, v92
	v_add_f32_e32 v97, v89, v97
	v_exp_f32_e32 v93, v93
	v_add_f32_e32 v97, v90, v97
	v_exp_f32_e32 v94, v94
	v_add_f32_e32 v97, v91, v97
	v_exp_f32_e32 v95, v95
	v_add_f32_e32 v97, v92, v97
	v_exp_f32_e32 v98, v64
	v_add_f32_e32 v64, v93, v97
	v_exp_f32_e32 v97, v65
	v_add_f32_e32 v64, v94, v64
	v_exp_f32_e32 v99, v66
	v_add_f32_e32 v64, v95, v64
	v_exp_f32_e32 v100, v67
	v_add_f32_e32 v64, v98, v64
	v_exp_f32_e32 v68, v68
	v_add_f32_e32 v64, v97, v64
	v_exp_f32_e32 v69, v69
	v_add_f32_e32 v64, v99, v64
	v_exp_f32_e32 v70, v70
	v_add_f32_e32 v64, v100, v64
	v_exp_f32_e32 v71, v71
	v_add_f32_e32 v64, v68, v64
	v_exp_f32_e32 v72, v72
	v_add_f32_e32 v64, v69, v64
	v_exp_f32_e32 v73, v73
	v_add_f32_e32 v64, v70, v64
	v_exp_f32_e32 v74, v74
	v_add_f32_e32 v64, v71, v64
	v_exp_f32_e32 v75, v75
	v_add_f32_e32 v64, v72, v64
	v_exp_f32_e32 v76, v76
	v_add_f32_e32 v64, v73, v64
	v_exp_f32_e32 v77, v77
	v_add_f32_e32 v64, v74, v64
	v_exp_f32_e32 v78, v78
	v_add_f32_e32 v64, v75, v64
	v_exp_f32_e32 v79, v79
	v_add_f32_e32 v64, v76, v64
	v_exp_f32_e32 v101, v48
	v_add_f32_e32 v48, v77, v64
	v_exp_f32_e32 v102, v49
	v_add_f32_e32 v48, v78, v48
	v_exp_f32_e32 v103, v50
	v_add_f32_e32 v48, v79, v48
	v_exp_f32_e32 v104, v51
	v_add_f32_e32 v48, v101, v48
	v_exp_f32_e32 v105, v52
	v_add_f32_e32 v48, v102, v48
	v_add_f32_e32 v48, v103, v48
	v_add_f32_e32 v48, v104, v48
	v_add_f32_e32 v106, v105, v48
	v_exp_f32_e32 v107, v53
	v_exp_f32_e32 v108, v54
	v_add3_u32 v110, s28, v142, v162
	v_exp_f32_e32 v109, v55
	ds_read2_b64 v[48:51], v110 offset1:2
	v_exp_f32_e32 v111, v56
	v_cvt_pk_bf16_f32 v52, v80, v81
	v_cvt_pk_bf16_f32 v53, v82, v83
	v_cvt_pk_bf16_f32 v54, v84, v85
	v_cvt_pk_bf16_f32 v55, v86, v87
	v_add_u32_e32 v80, 0x2000, v110
	ds_read2_b64 v[64:67], v80 offset0:32 offset1:34
	s_waitcnt lgkmcnt(1)
	v_mfma_f32_32x32x16_bf16 v[16:31], v[48:51], v[52:55], v[16:31]
	v_add_f32_e32 v48, v107, v106
	v_add_f32_e32 v48, v108, v48
	v_add_f32_e32 v48, v109, v48
	v_add_f32_e32 v56, v111, v48
	v_exp_f32_e32 v81, v57
	ds_read2_b64 v[48:51], v110 offset0:4 offset1:6
	s_waitcnt lgkmcnt(1)
	v_mfma_f32_32x32x16_bf16 v[0:15], v[64:67], v[52:55], v[0:15]
	v_exp_f32_e32 v82, v58
	v_cvt_pk_bf16_f32 v52, v88, v89
	v_cvt_pk_bf16_f32 v53, v90, v91
	v_cvt_pk_bf16_f32 v54, v92, v93
	v_cvt_pk_bf16_f32 v55, v94, v95
	ds_read2_b64 v[64:67], v80 offset0:36 offset1:38
	s_waitcnt lgkmcnt(1)
	v_mfma_f32_32x32x16_bf16 v[16:31], v[48:51], v[52:55], v[16:31]
	v_add_f32_e32 v48, v81, v56
	v_add_f32_e32 v83, v82, v48
	v_exp_f32_e32 v84, v59
	v_exp_f32_e32 v60, v60
	ds_read2_b64 v[48:51], v110 offset0:8 offset1:10
	s_waitcnt lgkmcnt(1)
	v_mfma_f32_32x32x16_bf16 v[0:15], v[64:67], v[52:55], v[0:15]
	v_exp_f32_e32 v61, v61
	v_cvt_pk_bf16_f32 v52, v98, v97
	v_cvt_pk_bf16_f32 v53, v99, v100
	v_cvt_pk_bf16_f32 v54, v68, v69
	v_cvt_pk_bf16_f32 v55, v70, v71
	ds_read2_b64 v[56:59], v80 offset0:40 offset1:42
	v_exp_f32_e32 v65, v32
	s_waitcnt lgkmcnt(1)
	v_mfma_f32_32x32x16_bf16 v[16:31], v[48:51], v[52:55], v[16:31]
	v_exp_f32_e32 v62, v62
	v_add_f32_e32 v48, v84, v83
	v_add_f32_e32 v48, v60, v48
	v_add_f32_e32 v48, v61, v48
	v_add_f32_e32 v64, v62, v48
	ds_read2_b64 v[48:51], v110 offset0:12 offset1:14
	s_waitcnt lgkmcnt(1)
	v_mfma_f32_32x32x16_bf16 v[0:15], v[56:59], v[52:55], v[0:15]
	ds_read2_b64 v[56:59], v80 offset0:44 offset1:46
	v_exp_f32_e32 v63, v63
	v_cvt_pk_bf16_f32 v52, v72, v73
	v_cvt_pk_bf16_f32 v53, v74, v75
	v_cvt_pk_bf16_f32 v54, v76, v77
	v_cvt_pk_bf16_f32 v55, v78, v79
	v_exp_f32_e32 v66, v33
	s_waitcnt lgkmcnt(1)
	v_mfma_f32_32x32x16_bf16 v[16:31], v[48:51], v[52:55], v[16:31]
	ds_read2_b64 v[48:51], v110 offset0:16 offset1:18
	v_mov_b32_e32 v32, v34
	v_cvt_pk_bf16_f32 v33, v103, v104
	v_cvt_pk_bf16_f32 v34, v105, v107
	s_waitcnt lgkmcnt(1)
	v_mfma_f32_32x32x16_bf16 v[0:15], v[56:59], v[52:55], v[0:15]
	ds_read2_b64 v[52:55], v80 offset0:48 offset1:50
	v_exp_f32_e32 v56, v32
	v_mov_b32_e32 v57, v35
	v_cvt_pk_bf16_f32 v32, v101, v102
	v_cvt_pk_bf16_f32 v35, v108, v109
	v_exp_f32_e32 v58, v36
	s_waitcnt lgkmcnt(1)
	v_mfma_f32_32x32x16_bf16 v[16:31], v[48:51], v[32:35], v[16:31]
	ds_read2_b64 v[48:51], v110 offset0:20 offset1:22
	v_exp_f32_e32 v59, v37
	v_exp_f32_e32 v57, v57
	v_exp_f32_e32 v46, v46
	v_add_f32_e32 v64, v63, v64
	s_lshl_b32 s8, s31, 7
	s_waitcnt lgkmcnt(1)
	v_mfma_f32_32x32x16_bf16 v[0:15], v[52:55], v[32:35], v[0:15]
	v_exp_f32_e32 v52, v38
	v_mov_b32_e32 v53, v39
	ds_read2_b64 v[36:39], v80 offset0:52 offset1:54
	v_cvt_pk_bf16_f32 v32, v111, v81
	v_cvt_pk_bf16_f32 v33, v82, v84
	v_cvt_pk_bf16_f32 v34, v60, v61
	v_cvt_pk_bf16_f32 v35, v62, v63
	v_exp_f32_e32 v53, v53
	v_exp_f32_e32 v54, v40
	s_waitcnt lgkmcnt(1)
	v_mfma_f32_32x32x16_bf16 v[16:31], v[48:51], v[32:35], v[16:31]
	ds_read2_b64 v[48:51], v110 offset0:24 offset1:26
	v_exp_f32_e32 v55, v41
	v_exp_f32_e32 v60, v42
	s_add_i32 s30, s30, s90
	s_waitcnt lgkmcnt(1)
	v_mfma_f32_32x32x16_bf16 v[0:15], v[36:39], v[32:35], v[0:15]
	ds_read2_b64 v[36:39], v80 offset0:56 offset1:58
	v_cvt_pk_bf16_f32 v32, v65, v66
	v_cvt_pk_bf16_f32 v33, v56, v57
	v_cvt_pk_bf16_f32 v34, v58, v59
	v_cvt_pk_bf16_f32 v35, v52, v53
	s_add_i32 s29, s29, s33
	s_cmpk_gt_i32 s30, 0xff
	s_waitcnt lgkmcnt(1)
	v_mfma_f32_32x32x16_bf16 v[16:31], v[48:51], v[32:35], v[16:31]
	v_exp_f32_e32 v48, v43
	v_exp_f32_e32 v44, v44
	v_exp_f32_e32 v45, v45
	ds_read2_b64 v[40:43], v110 offset0:28 offset1:30
	s_waitcnt lgkmcnt(1)
	v_mfma_f32_32x32x16_bf16 v[0:15], v[36:39], v[32:35], v[0:15]
	v_exp_f32_e32 v47, v47
	v_cvt_pk_bf16_f32 v32, v54, v55
	v_cvt_pk_bf16_f32 v33, v60, v48
	v_cvt_pk_bf16_f32 v34, v44, v45
	v_cvt_pk_bf16_f32 v35, v46, v47
	ds_read2_b64 v[36:39], v80 offset0:60 offset1:62
	s_waitcnt lgkmcnt(0)
	v_mfma_f32_32x32x16_bf16 v[16:31], v[40:43], v[32:35], v[16:31]
	v_add_f32_e32 v40, v65, v64
	v_add_f32_e32 v40, v66, v40
	v_add_f32_e32 v40, v56, v40
	v_add_f32_e32 v40, v57, v40
	v_add_f32_e32 v40, v58, v40
	v_add_f32_e32 v40, v59, v40
	v_add_f32_e32 v40, v52, v40
	v_add_f32_e32 v40, v53, v40
	v_add_f32_e32 v40, v54, v40
	v_add_f32_e32 v40, v55, v40
	v_add_f32_e32 v40, v60, v40
	v_add_f32_e32 v40, v48, v40
	v_add_f32_e32 v40, v44, v40
	v_add_f32_e32 v40, v45, v40
	v_add_f32_e32 v40, v46, v40
	v_add_f32_e32 v40, v47, v40
	v_add_f32_e32 v40, v149, v40
	ds_bpermute_b32 v41, v147, v40
	v_mfma_f32_32x32x16_bf16 v[0:15], v[36:39], v[32:35], v[0:15]
	s_barrier
	s_cselect_b32 s101, 1, 0
	s_cmp_lg_u32 s100, 0
	s_cbranch_scc1 .Latt0_nofin
	s_barrier

.Latt0_nostag:
	v_mov_b32_e32 v194, 0
	v_mov_b32_e32 v195, 0
	v_mov_b32_e32 v196, 0
	v_mov_b32_e32 v197, 0
	v_mov_b32_e32 v198, 0
	v_mov_b32_e32 v199, 0
	v_mov_b32_e32 v200, 0
	v_mov_b32_e32 v201, 0
	v_mov_b32_e32 v202, 0
	v_mov_b32_e32 v203, 0
	v_mov_b32_e32 v204, 0
	v_mov_b32_e32 v205, 0
	v_mov_b32_e32 v206, 0
	v_mov_b32_e32 v207, 0
	v_mov_b32_e32 v208, 0
	v_mov_b32_e32 v209, 0
	v_mov_b32_e32 v210, 0xff800000

.LBB0_665:
	s_mov_b32 s1, s98
	v_add3_u32 v171, s1, v169, v170
	ds_read_b128 v[32:35], v171
	ds_read_b128 v[174:177], v171 offset:32
	s_waitcnt lgkmcnt(1)
	v_mfma_f32_32x32x16_bf16 v[80:95], v[32:35], v[108:111], v[194:209]
	ds_read_b128 v[32:35], v171 offset:6656
	ds_read_b128 v[178:181], v171 offset:6688
	s_waitcnt lgkmcnt(1)
	v_mfma_f32_32x32x16_bf16 v[64:79], v[32:35], v[108:111], v[194:209]
	ds_read_b128 v[32:35], v171 offset:13312
	ds_read_b128 v[182:185], v171 offset:13344
	s_waitcnt lgkmcnt(1)
	v_mfma_f32_32x32x16_bf16 v[48:63], v[32:35], v[108:111], v[194:209]
	ds_read_b128 v[32:35], v171 offset:19968
	ds_read_b128 v[186:189], v171 offset:20000
	v_mfma_f32_32x32x16_bf16 v[80:95], v[174:177], v[104:107], v[80:95]
	s_waitcnt lgkmcnt(1)
	v_mfma_f32_32x32x16_bf16 v[32:47], v[32:35], v[108:111], v[194:209]
	v_mfma_f32_32x32x16_bf16 v[64:79], v[178:181], v[104:107], v[64:79]
	ds_read_b128 v[174:177], v171 offset:64
	ds_read_b128 v[178:181], v171 offset:96
	v_mfma_f32_32x32x16_bf16 v[48:63], v[182:185], v[104:107], v[48:63]
	s_waitcnt lgkmcnt(1)
	v_mfma_f32_32x32x16_bf16 v[80:95], v[174:177], v[100:103], v[80:95]
	ds_read_b128 v[174:177], v171 offset:6720
	ds_read_b128 v[182:185], v171 offset:6752
	v_mfma_f32_32x32x16_bf16 v[32:47], v[186:189], v[104:107], v[32:47]
	s_waitcnt lgkmcnt(1)
	v_mfma_f32_32x32x16_bf16 v[64:79], v[174:177], v[100:103], v[64:79]
	ds_read_b128 v[174:177], v171 offset:13376
	ds_read_b128 v[186:189], v171 offset:13408
	s_waitcnt lgkmcnt(1)
	v_mfma_f32_32x32x16_bf16 v[48:63], v[174:177], v[100:103], v[48:63]
	ds_read_b128 v[174:177], v171 offset:20032
	ds_read_b128 v[190:193], v171 offset:20064
	v_mfma_f32_32x32x16_bf16 v[80:95], v[178:181], v[96:99], v[80:95]
	s_waitcnt lgkmcnt(1)
	v_mfma_f32_32x32x16_bf16 v[32:47], v[174:177], v[100:103], v[32:47]
	ds_read_b128 v[174:177], v171 offset:128
	ds_read_b128 v[178:181], v171 offset:160
	s_waitcnt lgkmcnt(1)
	v_mfma_f32_32x32x16_bf16 v[80:95], v[174:177], v[112:115], v[80:95]
	v_mfma_f32_32x32x16_bf16 v[64:79], v[182:185], v[96:99], v[64:79]
	ds_read_b128 v[174:177], v171 offset:6784
	ds_read_b128 v[182:185], v171 offset:6816
	v_mfma_f32_32x32x16_bf16 v[48:63], v[186:189], v[96:99], v[48:63]
	s_waitcnt lgkmcnt(2)
	v_mfma_f32_32x32x16_bf16 v[80:95], v[178:181], v[116:119], v[80:95]
	s_waitcnt lgkmcnt(1)
	v_mfma_f32_32x32x16_bf16 v[64:79], v[174:177], v[112:115], v[64:79]
	ds_read_b128 v[174:177], v171 offset:13440
	ds_read_b128 v[186:189], v171 offset:13472
	s_nop 7
	v_max_f32_e32 v173, v80, v80
	s_waitcnt lgkmcnt(1)
	v_mfma_f32_32x32x16_bf16 v[48:63], v[174:177], v[112:115], v[48:63]
	ds_read_b128 v[174:177], v171 offset:20096
	ds_read_b128 v[178:181], v171 offset:20128
	v_max_f32_e32 v171, v81, v81
	v_max_f32_e32 v171, v173, v171
	v_max3_f32 v171, v171, v82, v83
	v_max3_f32 v171, v171, v84, v85
	v_max3_f32 v171, v171, v86, v87
	v_max3_f32 v171, v171, v88, v89
	v_mfma_f32_32x32x16_bf16 v[32:47], v[190:193], v[96:99], v[32:47]
	v_max3_f32 v171, v171, v90, v91
	v_max3_f32 v171, v171, v92, v93
	v_max3_f32 v171, v171, v94, v95
	v_mfma_f32_32x32x16_bf16 v[64:79], v[182:185], v[116:119], v[64:79]
	s_waitcnt lgkmcnt(2)
	v_mfma_f32_32x32x16_bf16 v[48:63], v[186:189], v[116:119], v[48:63]
	s_nop 9
	v_max3_f32 v171, v171, v64, v65
	v_max3_f32 v171, v171, v66, v67
	v_max3_f32 v171, v171, v68, v69
	v_max3_f32 v171, v171, v70, v71
	v_max3_f32 v171, v171, v72, v73
	v_max3_f32 v171, v171, v74, v75
	v_max3_f32 v171, v171, v76, v77
	s_waitcnt lgkmcnt(1)
	v_mfma_f32_32x32x16_bf16 v[32:47], v[174:177], v[112:115], v[32:47]
	v_max3_f32 v171, v171, v78, v79
	v_max3_f32 v171, v171, v48, v49
	v_max3_f32 v171, v171, v50, v51
	v_max3_f32 v171, v171, v52, v53
	v_max3_f32 v171, v171, v54, v55
	v_max3_f32 v171, v171, v56, v57
	v_max3_f32 v171, v171, v58, v59
	s_waitcnt lgkmcnt(0)
	v_mfma_f32_32x32x16_bf16 v[32:47], v[178:181], v[116:119], v[32:47]
	v_max3_f32 v171, v171, v60, v61
	v_max3_f32 v171, v171, v62, v63
	s_nop 9
	v_max3_f32 v171, v171, v32, v33
	v_max3_f32 v171, v171, v34, v35
	v_max3_f32 v171, v171, v36, v37
	v_max3_f32 v171, v171, v38, v39
	v_max3_f32 v171, v171, v40, v41
	v_max3_f32 v171, v171, v42, v43
	v_max3_f32 v171, v171, v44, v45
	v_max3_f32 v171, v171, v46, v47
	ds_bpermute_b32 v173, v147, v171
	s_waitcnt lgkmcnt(0)
	v_max_f32_e32 v171, v171, v173
	v_cmp_gt_f32_e32 vcc, v171, v210
	s_cbranch_vccz .LBB0_668
	s_nop 1
	v_cndmask_b32_e32 v171, 0, v171, vcc
	v_exp_f32_e64 v172, -v171
	v_sub_f32_e32 v194, v194, v171
	v_sub_f32_e32 v195, v195, v171
	v_sub_f32_e32 v196, v196, v171
	v_sub_f32_e32 v197, v197, v171
	v_sub_f32_e32 v198, v198, v171
	v_sub_f32_e32 v199, v199, v171
	v_sub_f32_e32 v200, v200, v171
	v_sub_f32_e32 v201, v201, v171
	v_sub_f32_e32 v202, v202, v171
	v_sub_f32_e32 v203, v203, v171
	v_sub_f32_e32 v204, v204, v171
	v_sub_f32_e32 v205, v205, v171
	v_sub_f32_e32 v206, v206, v171
	v_sub_f32_e32 v207, v207, v171
	v_sub_f32_e32 v208, v208, v171
	v_sub_f32_e32 v209, v209, v171
	v_pk_mul_f32 v[30:31], v[30:31], v[172:173] op_sel_hi:[1,0]
	v_pk_mul_f32 v[28:29], v[28:29], v[172:173] op_sel_hi:[1,0]
	v_pk_mul_f32 v[26:27], v[26:27], v[172:173] op_sel_hi:[1,0]
	v_pk_mul_f32 v[24:25], v[24:25], v[172:173] op_sel_hi:[1,0]
	v_pk_mul_f32 v[22:23], v[22:23], v[172:173] op_sel_hi:[1,0]
	v_pk_mul_f32 v[20:21], v[20:21], v[172:173] op_sel_hi:[1,0]
	v_pk_mul_f32 v[18:19], v[18:19], v[172:173] op_sel_hi:[1,0]
	v_pk_mul_f32 v[16:17], v[16:17], v[172:173] op_sel_hi:[1,0]
	v_pk_mul_f32 v[14:15], v[14:15], v[172:173] op_sel_hi:[1,0]
	v_pk_mul_f32 v[12:13], v[12:13], v[172:173] op_sel_hi:[1,0]
	v_pk_mul_f32 v[10:11], v[10:11], v[172:173] op_sel_hi:[1,0]
	v_pk_mul_f32 v[8:9], v[8:9], v[172:173] op_sel_hi:[1,0]
	v_pk_mul_f32 v[6:7], v[6:7], v[172:173] op_sel_hi:[1,0]
	v_pk_mul_f32 v[4:5], v[4:5], v[172:173] op_sel_hi:[1,0]
	v_pk_mul_f32 v[2:3], v[2:3], v[172:173] op_sel_hi:[1,0]
	v_pk_mul_f32 v[0:1], v[0:1], v[172:173] op_sel_hi:[1,0]
	v_mul_f32_e32 v149, v149, v172
	v_sub_f32_e32 v80, v80, v171
	v_sub_f32_e32 v81, v81, v171
	v_sub_f32_e32 v82, v82, v171
	v_sub_f32_e32 v83, v83, v171
	v_sub_f32_e32 v84, v84, v171
	v_sub_f32_e32 v85, v85, v171
	v_sub_f32_e32 v86, v86, v171
	v_sub_f32_e32 v87, v87, v171
	v_sub_f32_e32 v88, v88, v171
	v_sub_f32_e32 v89, v89, v171
	v_sub_f32_e32 v90, v90, v171
	v_sub_f32_e32 v91, v91, v171
	v_sub_f32_e32 v92, v92, v171
	v_sub_f32_e32 v93, v93, v171
	v_sub_f32_e32 v94, v94, v171
	v_sub_f32_e32 v95, v95, v171
	v_sub_f32_e32 v64, v64, v171
	v_sub_f32_e32 v65, v65, v171
	v_sub_f32_e32 v66, v66, v171
	v_sub_f32_e32 v67, v67, v171
	v_sub_f32_e32 v68, v68, v171
	v_sub_f32_e32 v69, v69, v171
	v_sub_f32_e32 v70, v70, v171
	v_sub_f32_e32 v71, v71, v171
	v_sub_f32_e32 v72, v72, v171
	v_sub_f32_e32 v73, v73, v171
	v_sub_f32_e32 v74, v74, v171
	v_sub_f32_e32 v75, v75, v171
	v_sub_f32_e32 v76, v76, v171
	v_sub_f32_e32 v77, v77, v171
	v_sub_f32_e32 v78, v78, v171
	v_sub_f32_e32 v79, v79, v171
	v_sub_f32_e32 v48, v48, v171
	v_sub_f32_e32 v49, v49, v171
	v_sub_f32_e32 v50, v50, v171
	v_sub_f32_e32 v51, v51, v171
	v_sub_f32_e32 v52, v52, v171
	v_sub_f32_e32 v53, v53, v171
	v_sub_f32_e32 v54, v54, v171
	v_sub_f32_e32 v55, v55, v171
	v_sub_f32_e32 v56, v56, v171
	v_sub_f32_e32 v57, v57, v171
	v_sub_f32_e32 v58, v58, v171
	v_sub_f32_e32 v59, v59, v171
	v_sub_f32_e32 v60, v60, v171
	v_sub_f32_e32 v61, v61, v171
	v_sub_f32_e32 v62, v62, v171
	v_sub_f32_e32 v63, v63, v171
	v_sub_f32_e32 v32, v32, v171
	v_sub_f32_e32 v33, v33, v171
	v_sub_f32_e32 v34, v34, v171
	v_sub_f32_e32 v35, v35, v171
	v_sub_f32_e32 v36, v36, v171
	v_sub_f32_e32 v37, v37, v171
	v_sub_f32_e32 v38, v38, v171
	v_sub_f32_e32 v39, v39, v171
	v_sub_f32_e32 v40, v40, v171
	v_sub_f32_e32 v41, v41, v171
	v_sub_f32_e32 v42, v42, v171
	v_sub_f32_e32 v43, v43, v171
	v_sub_f32_e32 v44, v44, v171
	v_sub_f32_e32 v45, v45, v171
	v_sub_f32_e32 v46, v46, v171
	v_sub_f32_e32 v47, v47, v171
	v_mov_b32_e32 v210, 0x41000000
.LBB0_668:
	s_waitcnt lgkmcnt(0)
	s_barrier
	v_exp_f32_e32 v80, v80
	v_exp_f32_e32 v81, v81
	v_exp_f32_e32 v82, v82
	v_exp_f32_e32 v83, v83
	v_add_f32_e32 v172, 0, v80
	v_exp_f32_e32 v84, v84
	v_add_f32_e32 v172, v81, v172
	v_exp_f32_e32 v85, v85
	v_add_f32_e32 v172, v82, v172
	v_exp_f32_e32 v86, v86
	v_add_f32_e32 v172, v83, v172
	v_exp_f32_e32 v87, v87
	v_add_f32_e32 v172, v84, v172
	v_exp_f32_e32 v88, v88
	v_add_f32_e32 v172, v85, v172
	v_exp_f32_e32 v89, v89
	v_add_f32_e32 v172, v86, v172
	v_exp_f32_e32 v90, v90
	v_add_f32_e32 v172, v87, v172
	v_exp_f32_e32 v91, v91
	v_add_f32_e32 v172, v88, v172
	v_exp_f32_e32 v92, v92
	v_add_f32_e32 v172, v89, v172
	v_exp_f32_e32 v93, v93
	v_add_f32_e32 v172, v90, v172
	v_exp_f32_e32 v94, v94
	v_add_f32_e32 v172, v91, v172
	v_exp_f32_e32 v95, v95
	v_add_f32_e32 v172, v92, v172
	v_exp_f32_e32 v173, v64
	v_add_f32_e32 v172, v93, v172
	v_exp_f32_e32 v174, v65
	v_add_f32_e32 v172, v94, v172
	v_exp_f32_e32 v175, v66
	v_add_f32_e32 v64, v95, v172
	v_exp_f32_e32 v172, v67
	v_add_f32_e32 v64, v173, v64
	v_exp_f32_e32 v176, v68
	v_add_f32_e32 v64, v174, v64
	v_exp_f32_e32 v177, v69
	v_add_f32_e32 v64, v175, v64
	v_exp_f32_e32 v178, v70
	v_add_f32_e32 v64, v172, v64
	v_exp_f32_e32 v179, v71
	v_add_f32_e32 v64, v176, v64
	v_exp_f32_e32 v72, v72
	v_add_f32_e32 v64, v177, v64
	v_exp_f32_e32 v73, v73
	v_add_f32_e32 v64, v178, v64
	v_exp_f32_e32 v74, v74
	v_add_f32_e32 v64, v179, v64
	v_exp_f32_e32 v75, v75
	v_add_f32_e32 v64, v72, v64
	v_exp_f32_e32 v76, v76
	v_add_f32_e32 v64, v73, v64
	v_exp_f32_e32 v77, v77
	v_add_f32_e32 v64, v74, v64
	v_exp_f32_e32 v78, v78
	v_add_f32_e32 v64, v75, v64
	v_exp_f32_e32 v79, v79
	v_add_f32_e32 v64, v76, v64
	v_exp_f32_e32 v180, v48
	v_add_f32_e32 v64, v77, v64
	v_exp_f32_e32 v181, v49
	v_add_f32_e32 v64, v78, v64
	v_exp_f32_e32 v182, v50
	v_add_f32_e32 v48, v79, v64
	v_add_f32_e32 v48, v180, v48
	v_add_f32_e32 v48, v181, v48
	v_add_f32_e32 v183, v182, v48
	v_exp_f32_e32 v184, v51
	v_mov_b32_e32 v48, v52
	v_add3_u32 v52, s1, v142, v162
	v_exp_f32_e32 v185, v48
	v_add_u32_e32 v187, 0x6800, v52
	v_exp_f32_e32 v186, v53
	ds_read2_b64 v[48:51], v187 offset1:2
	v_exp_f32_e32 v188, v54
	v_cvt_pk_bf16_f32 v64, v80, v81
	v_cvt_pk_bf16_f32 v65, v82, v83
	v_cvt_pk_bf16_f32 v66, v84, v85
	v_cvt_pk_bf16_f32 v67, v86, v87
	v_add_u32_e32 v80, 0x8800, v52
	ds_read2_b64 v[68:71], v80 offset0:32 offset1:34
	s_waitcnt lgkmcnt(1)
	v_mfma_f32_32x32x16_bf16 v[16:31], v[48:51], v[64:67], v[16:31]
	v_add_f32_e32 v48, v184, v183
	v_add_f32_e32 v48, v185, v48
	v_add_f32_e32 v48, v186, v48
	v_add_f32_e32 v81, v188, v48
	v_exp_f32_e32 v82, v55
	ds_read2_b64 v[48:51], v187 offset0:4 offset1:6
	s_waitcnt lgkmcnt(1)
	v_mfma_f32_32x32x16_bf16 v[0:15], v[68:71], v[64:67], v[0:15]
	v_exp_f32_e32 v68, v56
	v_cvt_pk_bf16_f32 v52, v88, v89
	v_cvt_pk_bf16_f32 v53, v90, v91
	v_cvt_pk_bf16_f32 v54, v92, v93
	v_cvt_pk_bf16_f32 v55, v94, v95
	ds_read2_b64 v[64:67], v80 offset0:36 offset1:38
	s_waitcnt lgkmcnt(1)
	v_mfma_f32_32x32x16_bf16 v[16:31], v[48:51], v[52:55], v[16:31]
	v_add_f32_e32 v48, v82, v81
	v_add_f32_e32 v69, v68, v48
	v_exp_f32_e32 v70, v57
	v_exp_f32_e32 v71, v58
	ds_read2_b64 v[48:51], v187 offset0:8 offset1:10
	s_waitcnt lgkmcnt(1)
	v_mfma_f32_32x32x16_bf16 v[0:15], v[64:67], v[52:55], v[0:15]
	v_mov_b32_e32 v52, v59
	ds_read2_b64 v[56:59], v80 offset0:40 offset1:42
	v_exp_f32_e32 v64, v52
	v_cvt_pk_bf16_f32 v52, v173, v174
	v_cvt_pk_bf16_f32 v53, v175, v172
	v_cvt_pk_bf16_f32 v54, v176, v177
	v_cvt_pk_bf16_f32 v55, v178, v179
	v_exp_f32_e32 v65, v32
	s_waitcnt lgkmcnt(1)
	v_mfma_f32_32x32x16_bf16 v[16:31], v[48:51], v[52:55], v[16:31]
	v_exp_f32_e32 v60, v60
	v_exp_f32_e32 v61, v61
	v_exp_f32_e32 v62, v62
	ds_read2_b64 v[48:51], v187 offset0:12 offset1:14
	s_waitcnt lgkmcnt(1)
	v_mfma_f32_32x32x16_bf16 v[0:15], v[56:59], v[52:55], v[0:15]
	ds_read2_b64 v[56:59], v80 offset0:44 offset1:46
	v_exp_f32_e32 v63, v63
	v_cvt_pk_bf16_f32 v52, v72, v73
	v_cvt_pk_bf16_f32 v53, v74, v75
	v_cvt_pk_bf16_f32 v54, v76, v77
	v_cvt_pk_bf16_f32 v55, v78, v79
	v_exp_f32_e32 v66, v33
	s_waitcnt lgkmcnt(1)
	v_mfma_f32_32x32x16_bf16 v[16:31], v[48:51], v[52:55], v[16:31]
	ds_read2_b64 v[48:51], v187 offset0:16 offset1:18
	v_exp_f32_e32 v67, v34
	v_mov_b32_e32 v32, v35
	v_cvt_pk_bf16_f32 v33, v182, v184
	v_cvt_pk_bf16_f32 v34, v185, v186
	v_cvt_pk_bf16_f32 v35, v188, v82
	s_waitcnt lgkmcnt(1)
	v_mfma_f32_32x32x16_bf16 v[0:15], v[56:59], v[52:55], v[0:15]
	ds_read2_b64 v[52:55], v80 offset0:48 offset1:50
	v_exp_f32_e32 v56, v32
	v_cvt_pk_bf16_f32 v32, v180, v181
	v_exp_f32_e32 v57, v36
	v_exp_f32_e32 v58, v37
	s_waitcnt lgkmcnt(1)
	v_mfma_f32_32x32x16_bf16 v[16:31], v[48:51], v[32:35], v[16:31]
	ds_read2_b64 v[48:51], v187 offset0:20 offset1:22
	v_exp_f32_e32 v59, v38
	v_lshl_add_u64 v[150:151], v[150:151], 0, s[14:15]
	v_lshl_add_u64 v[152:153], v[152:153], 0, s[14:15]
	v_lshl_add_u64 v[154:155], v[154:155], 0, s[12:13]
	v_lshl_add_u64 v[156:157], v[156:157], 0, s[12:13]
	s_waitcnt lgkmcnt(1)
	v_mfma_f32_32x32x16_bf16 v[0:15], v[52:55], v[32:35], v[0:15]
	v_mov_b32_e32 v32, v39
	ds_read2_b64 v[36:39], v80 offset0:52 offset1:54
	v_exp_f32_e32 v52, v32
	v_cvt_pk_bf16_f32 v32, v68, v70
	v_cvt_pk_bf16_f32 v33, v71, v64
	v_cvt_pk_bf16_f32 v34, v60, v61
	v_cvt_pk_bf16_f32 v35, v62, v63
	v_exp_f32_e32 v53, v40
	s_waitcnt lgkmcnt(1)
	v_mfma_f32_32x32x16_bf16 v[16:31], v[48:51], v[32:35], v[16:31]
	ds_read2_b64 v[48:51], v187 offset0:24 offset1:26
	v_exp_f32_e32 v54, v41
	v_exp_f32_e32 v55, v42
	v_exp_f32_e32 v44, v44
	s_waitcnt lgkmcnt(1)
	v_mfma_f32_32x32x16_bf16 v[0:15], v[36:39], v[32:35], v[0:15]
	ds_read2_b64 v[36:39], v80 offset0:56 offset1:58
	v_exp_f32_e32 v45, v45
	v_exp_f32_e32 v68, v43
	v_cvt_pk_bf16_f32 v32, v65, v66
	v_cvt_pk_bf16_f32 v33, v67, v56
	v_cvt_pk_bf16_f32 v34, v57, v58
	v_cvt_pk_bf16_f32 v35, v59, v52
	v_exp_f32_e32 v46, v46
	ds_read2_b64 v[40:43], v187 offset0:28 offset1:30
	s_waitcnt lgkmcnt(2)
	v_mfma_f32_32x32x16_bf16 v[16:31], v[48:51], v[32:35], v[16:31]
	s_cmp_lg_u32 s0, 33
	v_lshl_add_u64 v[158:159], v[158:159], 0, s[12:13]
	s_waitcnt lgkmcnt(1)
	v_mfma_f32_32x32x16_bf16 v[0:15], v[36:39], v[32:35], v[0:15]
	v_exp_f32_e32 v47, v47
	ds_read2_b64 v[36:39], v80 offset0:60 offset1:62
	v_cvt_pk_bf16_f32 v32, v53, v54
	v_cvt_pk_bf16_f32 v33, v55, v68
	v_cvt_pk_bf16_f32 v34, v44, v45
	v_cvt_pk_bf16_f32 v35, v46, v47
	s_waitcnt lgkmcnt(0)
	s_barrier
	v_mfma_f32_32x32x16_bf16 v[16:31], v[40:43], v[32:35], v[16:31]
	v_add_f32_e32 v40, v70, v69
	v_add_f32_e32 v40, v71, v40
	v_add_f32_e32 v40, v64, v40
	v_add_f32_e32 v40, v60, v40
	v_add_f32_e32 v40, v61, v40
	v_add_f32_e32 v40, v62, v40
	v_add_f32_e32 v40, v63, v40
	v_mfma_f32_32x32x16_bf16 v[0:15], v[36:39], v[32:35], v[0:15]
	v_add_f32_e32 v32, v65, v40
	v_add_f32_e32 v32, v66, v32
	v_add_f32_e32 v32, v67, v32
	v_add_f32_e32 v32, v56, v32
	v_add_f32_e32 v32, v57, v32
	v_add_f32_e32 v32, v58, v32
	v_add_f32_e32 v32, v59, v32
	v_add_f32_e32 v32, v52, v32
	v_add_f32_e32 v32, v53, v32
	v_add_f32_e32 v32, v54, v32
	v_add_f32_e32 v32, v55, v32
	v_add_f32_e32 v32, v68, v32
	v_add_f32_e32 v32, v44, v32
	v_add_f32_e32 v32, v45, v32
	v_add_f32_e32 v32, v46, v32
	v_add_f32_e32 v32, v47, v32
	v_add_f32_e32 v149, v149, v32
	s_cbranch_scc0 .LBB0_659
	v_mov_b32_e32 v172, v171
	s_mov_b32 s1, s0
	s_mov_b32 s98, s99
	s_add_i32 s99, s99, 0xaa00
	s_cmp_lt_u32 s99, 0x1fe00
	s_cselect_b32 s99, s99, 0
	s_branch .LBB0_663

.LBB0_2125:
	s_waitcnt lgkmcnt(0)
	s_barrier
	v_exp_f32_e32 v80, v80
	v_exp_f32_e32 v81, v81
	v_exp_f32_e32 v82, v82
	v_exp_f32_e32 v83, v83
	v_add_f32_e32 v97, 0, v80
	v_exp_f32_e32 v84, v84
	v_add_f32_e32 v97, v81, v97
	v_exp_f32_e32 v85, v85
	v_add_f32_e32 v97, v82, v97
	v_exp_f32_e32 v86, v86
	v_add_f32_e32 v97, v83, v97
	v_exp_f32_e32 v87, v87
	v_add_f32_e32 v97, v84, v97
	v_exp_f32_e32 v88, v88
	v_add_f32_e32 v97, v85, v97
	v_exp_f32_e32 v89, v89
	v_add_f32_e32 v97, v86, v97
	v_exp_f32_e32 v90, v90
	v_add_f32_e32 v97, v87, v97
	v_exp_f32_e32 v91, v91
	v_add_f32_e32 v97, v88, v97
	v_exp_f32_e32 v92, v92
	v_add_f32_e32 v97, v89, v97
	v_exp_f32_e32 v93, v93
	v_add_f32_e32 v97, v90, v97
	v_exp_f32_e32 v94, v94
	v_add_f32_e32 v97, v91, v97
	v_exp_f32_e32 v95, v95
	v_add_f32_e32 v97, v92, v97
	v_exp_f32_e32 v98, v64
	v_add_f32_e32 v64, v93, v97
	v_exp_f32_e32 v97, v65
	v_add_f32_e32 v64, v94, v64
	v_exp_f32_e32 v99, v66
	v_add_f32_e32 v64, v95, v64
	v_exp_f32_e32 v100, v67
	v_add_f32_e32 v64, v98, v64
	v_exp_f32_e32 v68, v68
	v_add_f32_e32 v64, v97, v64
	v_exp_f32_e32 v69, v69
	v_add_f32_e32 v64, v99, v64
	v_exp_f32_e32 v70, v70
	v_add_f32_e32 v64, v100, v64
	v_exp_f32_e32 v71, v71
	v_add_f32_e32 v64, v68, v64
	v_exp_f32_e32 v72, v72
	v_add_f32_e32 v64, v69, v64
	v_exp_f32_e32 v73, v73
	v_add_f32_e32 v64, v70, v64
	v_exp_f32_e32 v74, v74
	v_add_f32_e32 v64, v71, v64
	v_exp_f32_e32 v75, v75
	v_add_f32_e32 v64, v72, v64
	v_exp_f32_e32 v76, v76
	v_add_f32_e32 v64, v73, v64
	v_exp_f32_e32 v77, v77
	v_add_f32_e32 v64, v74, v64
	v_exp_f32_e32 v78, v78
	v_add_f32_e32 v64, v75, v64
	v_exp_f32_e32 v79, v79
	v_add_f32_e32 v64, v76, v64
	v_exp_f32_e32 v101, v48
	v_add_f32_e32 v48, v77, v64
	v_exp_f32_e32 v102, v49
	v_add_f32_e32 v48, v78, v48
	v_exp_f32_e32 v103, v50
	v_add_f32_e32 v48, v79, v48
	v_exp_f32_e32 v104, v51
	v_add_f32_e32 v48, v101, v48
	v_exp_f32_e32 v105, v52
	v_add_f32_e32 v48, v102, v48
	v_add_f32_e32 v48, v103, v48
	v_add_f32_e32 v48, v104, v48
	v_add_f32_e32 v106, v105, v48
	v_exp_f32_e32 v107, v53
	v_exp_f32_e32 v108, v54
	v_add3_u32 v110, s28, v142, v162
	v_exp_f32_e32 v109, v55
	ds_read2_b64 v[48:51], v110 offset1:2
	v_exp_f32_e32 v111, v56
	v_cvt_pk_bf16_f32 v52, v80, v81
	v_cvt_pk_bf16_f32 v53, v82, v83
	v_cvt_pk_bf16_f32 v54, v84, v85
	v_cvt_pk_bf16_f32 v55, v86, v87
	v_add_u32_e32 v80, 0x2000, v110
	ds_read2_b64 v[64:67], v80 offset0:32 offset1:34
	s_waitcnt lgkmcnt(1)
	v_mfma_f32_32x32x16_bf16 v[16:31], v[48:51], v[52:55], v[16:31]
	v_add_f32_e32 v48, v107, v106
	v_add_f32_e32 v48, v108, v48
	v_add_f32_e32 v48, v109, v48
	v_add_f32_e32 v56, v111, v48
	v_exp_f32_e32 v81, v57
	ds_read2_b64 v[48:51], v110 offset0:4 offset1:6
	s_waitcnt lgkmcnt(1)
	v_mfma_f32_32x32x16_bf16 v[0:15], v[64:67], v[52:55], v[0:15]
	v_exp_f32_e32 v82, v58
	v_cvt_pk_bf16_f32 v52, v88, v89
	v_cvt_pk_bf16_f32 v53, v90, v91
	v_cvt_pk_bf16_f32 v54, v92, v93
	v_cvt_pk_bf16_f32 v55, v94, v95
	ds_read2_b64 v[64:67], v80 offset0:36 offset1:38
	s_waitcnt lgkmcnt(1)
	v_mfma_f32_32x32x16_bf16 v[16:31], v[48:51], v[52:55], v[16:31]
	v_add_f32_e32 v48, v81, v56
	v_add_f32_e32 v83, v82, v48
	v_exp_f32_e32 v84, v59
	v_exp_f32_e32 v60, v60
	ds_read2_b64 v[48:51], v110 offset0:8 offset1:10
	s_waitcnt lgkmcnt(1)
	v_mfma_f32_32x32x16_bf16 v[0:15], v[64:67], v[52:55], v[0:15]
	v_exp_f32_e32 v61, v61
	v_cvt_pk_bf16_f32 v52, v98, v97
	v_cvt_pk_bf16_f32 v53, v99, v100
	v_cvt_pk_bf16_f32 v54, v68, v69
	v_cvt_pk_bf16_f32 v55, v70, v71
	ds_read2_b64 v[56:59], v80 offset0:40 offset1:42
	v_exp_f32_e32 v65, v32
	s_waitcnt lgkmcnt(1)
	v_mfma_f32_32x32x16_bf16 v[16:31], v[48:51], v[52:55], v[16:31]
	v_exp_f32_e32 v62, v62
	v_add_f32_e32 v48, v84, v83
	v_add_f32_e32 v48, v60, v48
	v_add_f32_e32 v48, v61, v48
	v_add_f32_e32 v64, v62, v48
	ds_read2_b64 v[48:51], v110 offset0:12 offset1:14
	s_waitcnt lgkmcnt(1)
	v_mfma_f32_32x32x16_bf16 v[0:15], v[56:59], v[52:55], v[0:15]
	ds_read2_b64 v[56:59], v80 offset0:44 offset1:46
	v_exp_f32_e32 v63, v63
	v_cvt_pk_bf16_f32 v52, v72, v73
	v_cvt_pk_bf16_f32 v53, v74, v75
	v_cvt_pk_bf16_f32 v54, v76, v77
	v_cvt_pk_bf16_f32 v55, v78, v79
	v_exp_f32_e32 v66, v33
	s_waitcnt lgkmcnt(1)
	v_mfma_f32_32x32x16_bf16 v[16:31], v[48:51], v[52:55], v[16:31]
	ds_read2_b64 v[48:51], v110 offset0:16 offset1:18
	v_mov_b32_e32 v32, v34
	v_cvt_pk_bf16_f32 v33, v103, v104
	v_cvt_pk_bf16_f32 v34, v105, v107
	s_waitcnt lgkmcnt(1)
	v_mfma_f32_32x32x16_bf16 v[0:15], v[56:59], v[52:55], v[0:15]
	ds_read2_b64 v[52:55], v80 offset0:48 offset1:50
	v_exp_f32_e32 v56, v32
	v_mov_b32_e32 v57, v35
	v_cvt_pk_bf16_f32 v32, v101, v102
	v_cvt_pk_bf16_f32 v35, v108, v109
	v_exp_f32_e32 v58, v36
	s_waitcnt lgkmcnt(1)
	v_mfma_f32_32x32x16_bf16 v[16:31], v[48:51], v[32:35], v[16:31]
	ds_read2_b64 v[48:51], v110 offset0:20 offset1:22
	v_exp_f32_e32 v59, v37
	v_exp_f32_e32 v57, v57
	v_exp_f32_e32 v46, v46
	v_add_f32_e32 v64, v63, v64
	s_lshl_b32 s10, s30, 7
	s_waitcnt lgkmcnt(1)
	v_mfma_f32_32x32x16_bf16 v[0:15], v[52:55], v[32:35], v[0:15]
	v_exp_f32_e32 v52, v38
	v_mov_b32_e32 v53, v39
	ds_read2_b64 v[36:39], v80 offset0:52 offset1:54
	v_cvt_pk_bf16_f32 v32, v111, v81
	v_cvt_pk_bf16_f32 v33, v82, v84
	v_cvt_pk_bf16_f32 v34, v60, v61
	v_cvt_pk_bf16_f32 v35, v62, v63
	v_exp_f32_e32 v53, v53
	v_exp_f32_e32 v54, v40
	s_waitcnt lgkmcnt(1)
	v_mfma_f32_32x32x16_bf16 v[16:31], v[48:51], v[32:35], v[16:31]
	ds_read2_b64 v[48:51], v110 offset0:24 offset1:26
	v_exp_f32_e32 v55, v41
	v_exp_f32_e32 v60, v42
	s_add_i32 s29, s29, s90
	s_waitcnt lgkmcnt(1)
	v_mfma_f32_32x32x16_bf16 v[0:15], v[36:39], v[32:35], v[0:15]
	ds_read2_b64 v[36:39], v80 offset0:56 offset1:58
	v_cvt_pk_bf16_f32 v32, v65, v66
	v_cvt_pk_bf16_f32 v33, v56, v57
	v_cvt_pk_bf16_f32 v34, v58, v59
	v_cvt_pk_bf16_f32 v35, v52, v53
	s_add_i32 s2, s37, s33
	s_cmpk_gt_i32 s29, 0xff
	s_waitcnt lgkmcnt(1)
	v_mfma_f32_32x32x16_bf16 v[16:31], v[48:51], v[32:35], v[16:31]
	v_exp_f32_e32 v48, v43
	v_exp_f32_e32 v44, v44
	v_exp_f32_e32 v45, v45
	ds_read2_b64 v[40:43], v110 offset0:28 offset1:30
	s_waitcnt lgkmcnt(1)
	v_mfma_f32_32x32x16_bf16 v[0:15], v[36:39], v[32:35], v[0:15]
	v_exp_f32_e32 v47, v47
	v_cvt_pk_bf16_f32 v32, v54, v55
	v_cvt_pk_bf16_f32 v33, v60, v48
	v_cvt_pk_bf16_f32 v34, v44, v45
	v_cvt_pk_bf16_f32 v35, v46, v47
	ds_read2_b64 v[36:39], v80 offset0:60 offset1:62
	s_waitcnt lgkmcnt(0)
	v_mfma_f32_32x32x16_bf16 v[16:31], v[40:43], v[32:35], v[16:31]
	v_add_f32_e32 v40, v65, v64
	v_add_f32_e32 v40, v66, v40
	v_add_f32_e32 v40, v56, v40
	v_add_f32_e32 v40, v57, v40
	v_add_f32_e32 v40, v58, v40
	v_add_f32_e32 v40, v59, v40
	v_add_f32_e32 v40, v52, v40
	v_add_f32_e32 v40, v53, v40
	v_add_f32_e32 v40, v54, v40
	v_add_f32_e32 v40, v55, v40
	v_add_f32_e32 v40, v60, v40
	v_add_f32_e32 v40, v48, v40
	v_add_f32_e32 v40, v44, v40
	v_add_f32_e32 v40, v45, v40
	v_add_f32_e32 v40, v46, v40
	v_add_f32_e32 v40, v47, v40
	v_add_f32_e32 v40, v149, v40
	ds_bpermute_b32 v41, v147, v40
	v_mfma_f32_32x32x16_bf16 v[0:15], v[36:39], v[32:35], v[0:15]
	s_barrier
	s_cselect_b32 s101, 1, 0
	s_cmp_lg_u32 s100, 0
	s_cbranch_scc1 .Latt1_nofin
	s_barrier

.LBB0_2129:
	s_mov_b32 s4, s98
	v_add3_u32 v171, s4, v169, v170
	ds_read_b128 v[32:35], v171
	ds_read_b128 v[174:177], v171 offset:32
	s_waitcnt lgkmcnt(1)
	v_mfma_f32_32x32x16_bf16 v[80:95], v[32:35], v[108:111], v[194:209]
	ds_read_b128 v[32:35], v171 offset:6656
	ds_read_b128 v[178:181], v171 offset:6688
	s_waitcnt lgkmcnt(1)
	v_mfma_f32_32x32x16_bf16 v[64:79], v[32:35], v[108:111], v[194:209]
	ds_read_b128 v[32:35], v171 offset:13312
	ds_read_b128 v[182:185], v171 offset:13344
	s_waitcnt lgkmcnt(1)
	v_mfma_f32_32x32x16_bf16 v[48:63], v[32:35], v[108:111], v[194:209]
	ds_read_b128 v[32:35], v171 offset:19968
	ds_read_b128 v[186:189], v171 offset:20000
	v_mfma_f32_32x32x16_bf16 v[80:95], v[174:177], v[104:107], v[80:95]
	s_waitcnt lgkmcnt(1)
	v_mfma_f32_32x32x16_bf16 v[32:47], v[32:35], v[108:111], v[194:209]
	v_mfma_f32_32x32x16_bf16 v[64:79], v[178:181], v[104:107], v[64:79]
	ds_read_b128 v[174:177], v171 offset:64
	ds_read_b128 v[178:181], v171 offset:96
	v_mfma_f32_32x32x16_bf16 v[48:63], v[182:185], v[104:107], v[48:63]
	s_waitcnt lgkmcnt(1)
	v_mfma_f32_32x32x16_bf16 v[80:95], v[174:177], v[100:103], v[80:95]
	ds_read_b128 v[174:177], v171 offset:6720
	ds_read_b128 v[182:185], v171 offset:6752
	v_mfma_f32_32x32x16_bf16 v[32:47], v[186:189], v[104:107], v[32:47]
	s_waitcnt lgkmcnt(1)
	v_mfma_f32_32x32x16_bf16 v[64:79], v[174:177], v[100:103], v[64:79]
	ds_read_b128 v[174:177], v171 offset:13376
	ds_read_b128 v[186:189], v171 offset:13408
	s_waitcnt lgkmcnt(1)
	v_mfma_f32_32x32x16_bf16 v[48:63], v[174:177], v[100:103], v[48:63]
	ds_read_b128 v[174:177], v171 offset:20032
	ds_read_b128 v[190:193], v171 offset:20064
	v_mfma_f32_32x32x16_bf16 v[80:95], v[178:181], v[96:99], v[80:95]
	s_waitcnt lgkmcnt(1)
	v_mfma_f32_32x32x16_bf16 v[32:47], v[174:177], v[100:103], v[32:47]
	ds_read_b128 v[174:177], v171 offset:128
	ds_read_b128 v[178:181], v171 offset:160
	s_waitcnt lgkmcnt(1)
	v_mfma_f32_32x32x16_bf16 v[80:95], v[174:177], v[112:115], v[80:95]
	v_mfma_f32_32x32x16_bf16 v[64:79], v[182:185], v[96:99], v[64:79]
	ds_read_b128 v[174:177], v171 offset:6784
	ds_read_b128 v[182:185], v171 offset:6816
	v_mfma_f32_32x32x16_bf16 v[48:63], v[186:189], v[96:99], v[48:63]
	s_waitcnt lgkmcnt(2)
	v_mfma_f32_32x32x16_bf16 v[80:95], v[178:181], v[116:119], v[80:95]
	s_waitcnt lgkmcnt(1)
	v_mfma_f32_32x32x16_bf16 v[64:79], v[174:177], v[112:115], v[64:79]
	ds_read_b128 v[174:177], v171 offset:13440
	ds_read_b128 v[186:189], v171 offset:13472
	s_nop 7
	v_max_f32_e32 v173, v80, v80
	s_waitcnt lgkmcnt(1)
	v_mfma_f32_32x32x16_bf16 v[48:63], v[174:177], v[112:115], v[48:63]
	ds_read_b128 v[174:177], v171 offset:20096
	ds_read_b128 v[178:181], v171 offset:20128
	v_max_f32_e32 v171, v81, v81
	v_max_f32_e32 v171, v173, v171
	v_max3_f32 v171, v171, v82, v83
	v_max3_f32 v171, v171, v84, v85
	v_max3_f32 v171, v171, v86, v87
	v_max3_f32 v171, v171, v88, v89
	v_mfma_f32_32x32x16_bf16 v[32:47], v[190:193], v[96:99], v[32:47]
	v_max3_f32 v171, v171, v90, v91
	v_max3_f32 v171, v171, v92, v93
	v_max3_f32 v171, v171, v94, v95
	v_mfma_f32_32x32x16_bf16 v[64:79], v[182:185], v[116:119], v[64:79]
	s_waitcnt lgkmcnt(2)
	v_mfma_f32_32x32x16_bf16 v[48:63], v[186:189], v[116:119], v[48:63]
	s_nop 9
	v_max3_f32 v171, v171, v64, v65
	v_max3_f32 v171, v171, v66, v67
	v_max3_f32 v171, v171, v68, v69
	v_max3_f32 v171, v171, v70, v71
	v_max3_f32 v171, v171, v72, v73
	v_max3_f32 v171, v171, v74, v75
	v_max3_f32 v171, v171, v76, v77
	s_waitcnt lgkmcnt(1)
	v_mfma_f32_32x32x16_bf16 v[32:47], v[174:177], v[112:115], v[32:47]
	v_max3_f32 v171, v171, v78, v79
	v_max3_f32 v171, v171, v48, v49
	v_max3_f32 v171, v171, v50, v51
	v_max3_f32 v171, v171, v52, v53
	v_max3_f32 v171, v171, v54, v55
	v_max3_f32 v171, v171, v56, v57
	v_max3_f32 v171, v171, v58, v59
	s_waitcnt lgkmcnt(0)
	v_mfma_f32_32x32x16_bf16 v[32:47], v[178:181], v[116:119], v[32:47]
	v_max3_f32 v171, v171, v60, v61
	v_max3_f32 v171, v171, v62, v63
	s_nop 9
	v_max3_f32 v171, v171, v32, v33
	v_max3_f32 v171, v171, v34, v35
	v_max3_f32 v171, v171, v36, v37
	v_max3_f32 v171, v171, v38, v39
	v_max3_f32 v171, v171, v40, v41
	v_max3_f32 v171, v171, v42, v43
	v_max3_f32 v171, v171, v44, v45
	v_max3_f32 v171, v171, v46, v47
	ds_bpermute_b32 v173, v147, v171
	s_waitcnt lgkmcnt(0)
	v_max_f32_e32 v171, v171, v173
	v_cmp_gt_f32_e32 vcc, v171, v210
	s_cbranch_vccz .LBB0_2132
	s_nop 1
	v_cndmask_b32_e32 v171, 0, v171, vcc
	v_exp_f32_e64 v172, -v171
	v_sub_f32_e32 v194, v194, v171
	v_sub_f32_e32 v195, v195, v171
	v_sub_f32_e32 v196, v196, v171
	v_sub_f32_e32 v197, v197, v171
	v_sub_f32_e32 v198, v198, v171
	v_sub_f32_e32 v199, v199, v171
	v_sub_f32_e32 v200, v200, v171
	v_sub_f32_e32 v201, v201, v171
	v_sub_f32_e32 v202, v202, v171
	v_sub_f32_e32 v203, v203, v171
	v_sub_f32_e32 v204, v204, v171
	v_sub_f32_e32 v205, v205, v171
	v_sub_f32_e32 v206, v206, v171
	v_sub_f32_e32 v207, v207, v171
	v_sub_f32_e32 v208, v208, v171
	v_sub_f32_e32 v209, v209, v171
	v_pk_mul_f32 v[30:31], v[30:31], v[172:173] op_sel_hi:[1,0]
	v_pk_mul_f32 v[28:29], v[28:29], v[172:173] op_sel_hi:[1,0]
	v_pk_mul_f32 v[26:27], v[26:27], v[172:173] op_sel_hi:[1,0]
	v_pk_mul_f32 v[24:25], v[24:25], v[172:173] op_sel_hi:[1,0]
	v_pk_mul_f32 v[22:23], v[22:23], v[172:173] op_sel_hi:[1,0]
	v_pk_mul_f32 v[20:21], v[20:21], v[172:173] op_sel_hi:[1,0]
	v_pk_mul_f32 v[18:19], v[18:19], v[172:173] op_sel_hi:[1,0]
	v_pk_mul_f32 v[16:17], v[16:17], v[172:173] op_sel_hi:[1,0]
	v_pk_mul_f32 v[14:15], v[14:15], v[172:173] op_sel_hi:[1,0]
	v_pk_mul_f32 v[12:13], v[12:13], v[172:173] op_sel_hi:[1,0]
	v_pk_mul_f32 v[10:11], v[10:11], v[172:173] op_sel_hi:[1,0]
	v_pk_mul_f32 v[8:9], v[8:9], v[172:173] op_sel_hi:[1,0]
	v_pk_mul_f32 v[6:7], v[6:7], v[172:173] op_sel_hi:[1,0]
	v_pk_mul_f32 v[4:5], v[4:5], v[172:173] op_sel_hi:[1,0]
	v_pk_mul_f32 v[2:3], v[2:3], v[172:173] op_sel_hi:[1,0]
	v_pk_mul_f32 v[0:1], v[0:1], v[172:173] op_sel_hi:[1,0]
	v_mul_f32_e32 v149, v149, v172
	v_sub_f32_e32 v80, v80, v171
	v_sub_f32_e32 v81, v81, v171
	v_sub_f32_e32 v82, v82, v171
	v_sub_f32_e32 v83, v83, v171
	v_sub_f32_e32 v84, v84, v171
	v_sub_f32_e32 v85, v85, v171
	v_sub_f32_e32 v86, v86, v171
	v_sub_f32_e32 v87, v87, v171
	v_sub_f32_e32 v88, v88, v171
	v_sub_f32_e32 v89, v89, v171
	v_sub_f32_e32 v90, v90, v171
	v_sub_f32_e32 v91, v91, v171
	v_sub_f32_e32 v92, v92, v171
	v_sub_f32_e32 v93, v93, v171
	v_sub_f32_e32 v94, v94, v171
	v_sub_f32_e32 v95, v95, v171
	v_sub_f32_e32 v64, v64, v171
	v_sub_f32_e32 v65, v65, v171
	v_sub_f32_e32 v66, v66, v171
	v_sub_f32_e32 v67, v67, v171
	v_sub_f32_e32 v68, v68, v171
	v_sub_f32_e32 v69, v69, v171
	v_sub_f32_e32 v70, v70, v171
	v_sub_f32_e32 v71, v71, v171
	v_sub_f32_e32 v72, v72, v171
	v_sub_f32_e32 v73, v73, v171
	v_sub_f32_e32 v74, v74, v171
	v_sub_f32_e32 v75, v75, v171
	v_sub_f32_e32 v76, v76, v171
	v_sub_f32_e32 v77, v77, v171
	v_sub_f32_e32 v78, v78, v171
	v_sub_f32_e32 v79, v79, v171
	v_sub_f32_e32 v48, v48, v171
	v_sub_f32_e32 v49, v49, v171
	v_sub_f32_e32 v50, v50, v171
	v_sub_f32_e32 v51, v51, v171
	v_sub_f32_e32 v52, v52, v171
	v_sub_f32_e32 v53, v53, v171
	v_sub_f32_e32 v54, v54, v171
	v_sub_f32_e32 v55, v55, v171
	v_sub_f32_e32 v56, v56, v171
	v_sub_f32_e32 v57, v57, v171
	v_sub_f32_e32 v58, v58, v171
	v_sub_f32_e32 v59, v59, v171
	v_sub_f32_e32 v60, v60, v171
	v_sub_f32_e32 v61, v61, v171
	v_sub_f32_e32 v62, v62, v171
	v_sub_f32_e32 v63, v63, v171
	v_sub_f32_e32 v32, v32, v171
	v_sub_f32_e32 v33, v33, v171
	v_sub_f32_e32 v34, v34, v171
	v_sub_f32_e32 v35, v35, v171
	v_sub_f32_e32 v36, v36, v171
	v_sub_f32_e32 v37, v37, v171
	v_sub_f32_e32 v38, v38, v171
	v_sub_f32_e32 v39, v39, v171
	v_sub_f32_e32 v40, v40, v171
	v_sub_f32_e32 v41, v41, v171
	v_sub_f32_e32 v42, v42, v171
	v_sub_f32_e32 v43, v43, v171
	v_sub_f32_e32 v44, v44, v171
	v_sub_f32_e32 v45, v45, v171
	v_sub_f32_e32 v46, v46, v171
	v_sub_f32_e32 v47, v47, v171
	v_mov_b32_e32 v210, 0x41000000
.LBB0_2132:
	s_waitcnt lgkmcnt(0)
	s_barrier
	v_exp_f32_e32 v80, v80
	v_exp_f32_e32 v81, v81
	v_exp_f32_e32 v82, v82
	v_exp_f32_e32 v83, v83
	v_add_f32_e32 v172, 0, v80
	v_exp_f32_e32 v84, v84
	v_add_f32_e32 v172, v81, v172
	v_exp_f32_e32 v85, v85
	v_add_f32_e32 v172, v82, v172
	v_exp_f32_e32 v86, v86
	v_add_f32_e32 v172, v83, v172
	v_exp_f32_e32 v87, v87
	v_add_f32_e32 v172, v84, v172
	v_exp_f32_e32 v88, v88
	v_add_f32_e32 v172, v85, v172
	v_exp_f32_e32 v89, v89
	v_add_f32_e32 v172, v86, v172
	v_exp_f32_e32 v90, v90
	v_add_f32_e32 v172, v87, v172
	v_exp_f32_e32 v91, v91
	v_add_f32_e32 v172, v88, v172
	v_exp_f32_e32 v92, v92
	v_add_f32_e32 v172, v89, v172
	v_exp_f32_e32 v93, v93
	v_add_f32_e32 v172, v90, v172
	v_exp_f32_e32 v94, v94
	v_add_f32_e32 v172, v91, v172
	v_exp_f32_e32 v95, v95
	v_add_f32_e32 v172, v92, v172
	v_exp_f32_e32 v173, v64
	v_add_f32_e32 v172, v93, v172
	v_exp_f32_e32 v174, v65
	v_add_f32_e32 v172, v94, v172
	v_exp_f32_e32 v175, v66
	v_add_f32_e32 v64, v95, v172
	v_exp_f32_e32 v172, v67
	v_add_f32_e32 v64, v173, v64
	v_exp_f32_e32 v176, v68
	v_add_f32_e32 v64, v174, v64
	v_exp_f32_e32 v177, v69
	v_add_f32_e32 v64, v175, v64
	v_exp_f32_e32 v178, v70
	v_add_f32_e32 v64, v172, v64
	v_exp_f32_e32 v179, v71
	v_add_f32_e32 v64, v176, v64
	v_exp_f32_e32 v72, v72
	v_add_f32_e32 v64, v177, v64
	v_exp_f32_e32 v73, v73
	v_add_f32_e32 v64, v178, v64
	v_exp_f32_e32 v74, v74
	v_add_f32_e32 v64, v179, v64
	v_exp_f32_e32 v75, v75
	v_add_f32_e32 v64, v72, v64
	v_exp_f32_e32 v76, v76
	v_add_f32_e32 v64, v73, v64
	v_exp_f32_e32 v77, v77
	v_add_f32_e32 v64, v74, v64
	v_exp_f32_e32 v78, v78
	v_add_f32_e32 v64, v75, v64
	v_exp_f32_e32 v79, v79
	v_add_f32_e32 v64, v76, v64
	v_exp_f32_e32 v180, v48
	v_add_f32_e32 v64, v77, v64
	v_exp_f32_e32 v181, v49
	v_add_f32_e32 v64, v78, v64
	v_exp_f32_e32 v182, v50
	v_add_f32_e32 v48, v79, v64
	v_add_f32_e32 v48, v180, v48
	v_add_f32_e32 v48, v181, v48
	v_add_f32_e32 v183, v182, v48
	v_exp_f32_e32 v184, v51
	v_mov_b32_e32 v48, v52
	v_add3_u32 v52, s4, v142, v162
	v_exp_f32_e32 v185, v48
	v_add_u32_e32 v187, 0x6800, v52
	v_exp_f32_e32 v186, v53
	ds_read2_b64 v[48:51], v187 offset1:2
	v_exp_f32_e32 v188, v54
	v_cvt_pk_bf16_f32 v64, v80, v81
	v_cvt_pk_bf16_f32 v65, v82, v83
	v_cvt_pk_bf16_f32 v66, v84, v85
	v_cvt_pk_bf16_f32 v67, v86, v87
	v_add_u32_e32 v80, 0x8800, v52
	ds_read2_b64 v[68:71], v80 offset0:32 offset1:34
	s_waitcnt lgkmcnt(1)
	v_mfma_f32_32x32x16_bf16 v[16:31], v[48:51], v[64:67], v[16:31]
	v_add_f32_e32 v48, v184, v183
	v_add_f32_e32 v48, v185, v48
	v_add_f32_e32 v48, v186, v48
	v_add_f32_e32 v81, v188, v48
	v_exp_f32_e32 v82, v55
	ds_read2_b64 v[48:51], v187 offset0:4 offset1:6
	s_waitcnt lgkmcnt(1)
	v_mfma_f32_32x32x16_bf16 v[0:15], v[68:71], v[64:67], v[0:15]
	v_exp_f32_e32 v68, v56
	v_cvt_pk_bf16_f32 v52, v88, v89
	v_cvt_pk_bf16_f32 v53, v90, v91
	v_cvt_pk_bf16_f32 v54, v92, v93
	v_cvt_pk_bf16_f32 v55, v94, v95
	ds_read2_b64 v[64:67], v80 offset0:36 offset1:38
	s_waitcnt lgkmcnt(1)
	v_mfma_f32_32x32x16_bf16 v[16:31], v[48:51], v[52:55], v[16:31]
	v_add_f32_e32 v48, v82, v81
	v_add_f32_e32 v69, v68, v48
	v_exp_f32_e32 v70, v57
	v_exp_f32_e32 v71, v58
	ds_read2_b64 v[48:51], v187 offset0:8 offset1:10
	s_waitcnt lgkmcnt(1)
	v_mfma_f32_32x32x16_bf16 v[0:15], v[64:67], v[52:55], v[0:15]
	v_mov_b32_e32 v52, v59
	ds_read2_b64 v[56:59], v80 offset0:40 offset1:42
	v_exp_f32_e32 v64, v52
	v_cvt_pk_bf16_f32 v52, v173, v174
	v_cvt_pk_bf16_f32 v53, v175, v172
	v_cvt_pk_bf16_f32 v54, v176, v177
	v_cvt_pk_bf16_f32 v55, v178, v179
	v_exp_f32_e32 v65, v32
	s_waitcnt lgkmcnt(1)
	v_mfma_f32_32x32x16_bf16 v[16:31], v[48:51], v[52:55], v[16:31]
	v_exp_f32_e32 v60, v60
	v_exp_f32_e32 v61, v61
	v_exp_f32_e32 v62, v62
	ds_read2_b64 v[48:51], v187 offset0:12 offset1:14
	s_waitcnt lgkmcnt(1)
	v_mfma_f32_32x32x16_bf16 v[0:15], v[56:59], v[52:55], v[0:15]
	ds_read2_b64 v[56:59], v80 offset0:44 offset1:46
	v_exp_f32_e32 v63, v63
	v_cvt_pk_bf16_f32 v52, v72, v73
	v_cvt_pk_bf16_f32 v53, v74, v75
	v_cvt_pk_bf16_f32 v54, v76, v77
	v_cvt_pk_bf16_f32 v55, v78, v79
	v_exp_f32_e32 v66, v33
	s_waitcnt lgkmcnt(1)
	v_mfma_f32_32x32x16_bf16 v[16:31], v[48:51], v[52:55], v[16:31]
	ds_read2_b64 v[48:51], v187 offset0:16 offset1:18
	v_exp_f32_e32 v67, v34
	v_mov_b32_e32 v32, v35
	v_cvt_pk_bf16_f32 v33, v182, v184
	v_cvt_pk_bf16_f32 v34, v185, v186
	v_cvt_pk_bf16_f32 v35, v188, v82
	s_waitcnt lgkmcnt(1)
	v_mfma_f32_32x32x16_bf16 v[0:15], v[56:59], v[52:55], v[0:15]
	ds_read2_b64 v[52:55], v80 offset0:48 offset1:50
	v_exp_f32_e32 v56, v32
	v_cvt_pk_bf16_f32 v32, v180, v181
	v_exp_f32_e32 v57, v36
	v_exp_f32_e32 v58, v37
	s_waitcnt lgkmcnt(1)
	v_mfma_f32_32x32x16_bf16 v[16:31], v[48:51], v[32:35], v[16:31]
	ds_read2_b64 v[48:51], v187 offset0:20 offset1:22
	v_exp_f32_e32 v59, v38
	v_lshl_add_u64 v[150:151], v[150:151], 0, s[16:17]
	v_lshl_add_u64 v[152:153], v[152:153], 0, s[16:17]
	v_lshl_add_u64 v[154:155], v[154:155], 0, s[14:15]
	v_lshl_add_u64 v[156:157], v[156:157], 0, s[14:15]
	s_waitcnt lgkmcnt(1)
	v_mfma_f32_32x32x16_bf16 v[0:15], v[52:55], v[32:35], v[0:15]
	v_mov_b32_e32 v32, v39
	ds_read2_b64 v[36:39], v80 offset0:52 offset1:54
	v_exp_f32_e32 v52, v32
	v_cvt_pk_bf16_f32 v32, v68, v70
	v_cvt_pk_bf16_f32 v33, v71, v64
	v_cvt_pk_bf16_f32 v34, v60, v61
	v_cvt_pk_bf16_f32 v35, v62, v63
	v_exp_f32_e32 v53, v40
	s_waitcnt lgkmcnt(1)
	v_mfma_f32_32x32x16_bf16 v[16:31], v[48:51], v[32:35], v[16:31]
	ds_read2_b64 v[48:51], v187 offset0:24 offset1:26
	v_exp_f32_e32 v54, v41
	v_exp_f32_e32 v55, v42
	v_exp_f32_e32 v44, v44
	s_waitcnt lgkmcnt(1)
	v_mfma_f32_32x32x16_bf16 v[0:15], v[36:39], v[32:35], v[0:15]
	ds_read2_b64 v[36:39], v80 offset0:56 offset1:58
	v_exp_f32_e32 v45, v45
	v_exp_f32_e32 v68, v43
	v_cvt_pk_bf16_f32 v32, v65, v66
	v_cvt_pk_bf16_f32 v33, v67, v56
	v_cvt_pk_bf16_f32 v34, v57, v58
	v_cvt_pk_bf16_f32 v35, v59, v52
	v_exp_f32_e32 v46, v46
	ds_read2_b64 v[40:43], v187 offset0:28 offset1:30
	s_waitcnt lgkmcnt(2)
	v_mfma_f32_32x32x16_bf16 v[16:31], v[48:51], v[32:35], v[16:31]
	s_cmp_lg_u32 s2, 33
	v_lshl_add_u64 v[158:159], v[158:159], 0, s[14:15]
	s_waitcnt lgkmcnt(1)
	v_mfma_f32_32x32x16_bf16 v[0:15], v[36:39], v[32:35], v[0:15]
	v_exp_f32_e32 v47, v47
	ds_read2_b64 v[36:39], v80 offset0:60 offset1:62
	v_cvt_pk_bf16_f32 v32, v53, v54
	v_cvt_pk_bf16_f32 v33, v55, v68
	v_cvt_pk_bf16_f32 v34, v44, v45
	v_cvt_pk_bf16_f32 v35, v46, v47
	s_waitcnt lgkmcnt(0)
	s_barrier
	v_mfma_f32_32x32x16_bf16 v[16:31], v[40:43], v[32:35], v[16:31]
	v_add_f32_e32 v40, v70, v69
	v_add_f32_e32 v40, v71, v40
	v_add_f32_e32 v40, v64, v40
	v_add_f32_e32 v40, v60, v40
	v_add_f32_e32 v40, v61, v40
	v_add_f32_e32 v40, v62, v40
	v_add_f32_e32 v40, v63, v40
	v_mfma_f32_32x32x16_bf16 v[0:15], v[36:39], v[32:35], v[0:15]
	v_add_f32_e32 v32, v65, v40
	v_add_f32_e32 v32, v66, v32
	v_add_f32_e32 v32, v67, v32
	v_add_f32_e32 v32, v56, v32
	v_add_f32_e32 v32, v57, v32
	v_add_f32_e32 v32, v58, v32
	v_add_f32_e32 v32, v59, v32
	v_add_f32_e32 v32, v52, v32
	v_add_f32_e32 v32, v53, v32
	v_add_f32_e32 v32, v54, v32
	v_add_f32_e32 v32, v55, v32
	v_add_f32_e32 v32, v68, v32
	v_add_f32_e32 v32, v44, v32
	v_add_f32_e32 v32, v45, v32
	v_add_f32_e32 v32, v46, v32
	v_add_f32_e32 v32, v47, v32
	v_add_f32_e32 v149, v149, v32
	s_cbranch_scc0 .LBB0_2123
	v_mov_b32_e32 v172, v171
	s_mov_b32 s4, s2
	s_mov_b32 s98, s99
	s_add_i32 s99, s99, 0xaa00
	s_cmp_lt_u32 s99, 0x1fe00
	s_cselect_b32 s99, s99, 0
	s_branch .LBB0_2127
